# scan phase: priority raise kept only for the two GDN recurrence waves, RWKV recurrence waves run at the helpers' priority (static-priority lever applied per role), on top of v86
# baseline (speedup 1.0000x reference)
.LBB0_1230:
	s_movk_i32 s50, 0x1600
	s_or_b64 exec, exec, s[2:3]
	v_readlane_b32 s0, v251, 0
	s_cmp_lt_i32 s0, 4
	s_cselect_b64 s[92:93], -1, 0
	s_cmp_gt_i32 s0, 3
	s_waitcnt lgkmcnt(0)
	s_barrier
	s_cbranch_scc1 .LBB0_1232
	s_cmp_gt_i32 s0, 1
	s_cbranch_scc1 .LBB0_1232
	s_setprio 3
